# nt hint removed from the 128 f32 weight loads of the bf16 conversion in P0/P1
# baseline (speedup 1.0000x reference)
; __device__ __forceinline__ void tr_load(const TrDesc& d, int lane, TrRegs& t) {
;     const int nblk = d.N / 32, kb = d.item / nblk, nb = d.item - kb * nblk, k0 = 64 * kb, n0 = 32 * nb;
;     const float* src = d.W + (size_t)(k0 + (lane >> 5)) * d.N + n0 + (lane & 31);
; #pragma unroll
;     for (int i = 0; i < 32; ++i) t.v[i] = __builtin_nontemporal_load(src + (size_t)(2 * i) * d.N);
;     const int c = lane & 7;
;     t.g0 = (f32x4){1.f, 1.f, 1.f, 1.f}; t.g1 = t.g0;
;     if (d.gs) { t.g0 = *(const f32x4*)(d.gs + k0 + 8 * c); t.g1 = *(const f32x4*)(d.gs + k0 + 8 * c + 4); }
; }
; __global__ void __launch_bounds__(NWAVES * 64, 2) hymba_fwd(Args a) {
;     ...
;             constexpr int NITEMS = I_IN;
;     ...
;             TrDesc dc, dn; TrRegs tc, tn;
;             const int NCW = (G - NG) * NWAVES; int it = (bx - NG) * NWAVES + wave;
;             if (it < NITEMS) { EARLY_DESC(dc, it); tr_load(dc, lane, tc); }
.LBB0_15:
	s_or_b64 exec, exec, s[4:5]
	s_load_dwordx16 s[56:71], s[0:1], 0x0
	s_waitcnt lgkmcnt(0)
	v_and_b32_e32 v251, 0xff, v0
	v_lshl_add_u32 v250, s86, 8, v251
	v_lshlrev_b32_e32 v250, 2, v250
	global_load_dword v252, v250, s[58:59]
	v_mov_b32_e32 v22, v0
	s_add_u32 s12, s94, 0x200000
	s_addc_u32 s13, s95, 0
	v_readfirstlane_b32 s3, v22
	s_ashr_i32 s19, s3, 6
	s_cmp_lt_i32 s2, 64
	s_cselect_b64 s[14:15], -1, 0
	s_cmp_gt_i32 s2, 63
	v_and_b32_e32 v32, 63, v22
	s_cbranch_scc0 .LBB0_19
	s_add_i32 s8, s18, s19
	s_add_i32 s16, s8, 0xfffffe00
	s_cmpk_lt_i32 s16, 0xa00
	s_cselect_b64 s[4:5], -1, 0
	s_cmpk_gt_i32 s16, 0x9ff
	v_lshrrev_b32_e32 v1, 5, v32
	v_and_b32_e32 v10, 31, v22
	s_cbranch_scc1 .LBB0_20
	s_mul_hi_i32 s3, s16, 0x66666667
	s_lshr_b32 s6, s3, 31
	s_ashr_i32 s3, s3, 5
	s_add_i32 s3, s3, s6
	s_mul_i32 s6, s3, 0xffffffb0
	s_add_i32 s7, s6, s16
	s_lshl_b32 s6, s3, 6
	s_lshl_b32 s10, s7, 5
	v_or_b32_e32 v4, s6, v1
	s_movk_i32 s3, 0x2800
	s_waitcnt lgkmcnt(0)
	v_mov_b64_e32 v[2:3], s[62:63]
	v_mad_i64_i32 v[2:3], s[20:21], v4, s3, v[2:3]
	s_ashr_i32 s11, s10, 31
	v_lshl_add_u64 v[2:3], s[10:11], 2, v[2:3]
	v_lshlrev_b32_e32 v4, 2, v10
	v_mov_b32_e32 v5, 0
	v_lshl_add_u64 v[2:3], v[2:3], 0, v[4:5]
	s_movk_i32 s3, 0x5000
	v_add_co_u32_e32 v4, vcc, s3, v2
	s_mov_b32 s3, 0xa000
	s_nop 0
	v_addc_co_u32_e32 v5, vcc, 0, v3, vcc
	v_add_co_u32_e32 v6, vcc, s3, v2
	s_mov_b32 s3, 0xf000
	s_nop 0
	v_addc_co_u32_e32 v7, vcc, 0, v3, vcc
	v_add_co_u32_e32 v8, vcc, s3, v2
	s_mov_b32 s3, 0x14000
	s_nop 0
	v_addc_co_u32_e32 v9, vcc, 0, v3, vcc
	v_add_co_u32_e32 v12, vcc, s3, v2
	s_mov_b32 s3, 0x19000
	s_nop 0
	v_addc_co_u32_e32 v13, vcc, 0, v3, vcc
	v_add_co_u32_e32 v14, vcc, s3, v2
	s_mov_b32 s3, 0x1e000
	s_nop 0
	v_addc_co_u32_e32 v15, vcc, 0, v3, vcc
	v_add_co_u32_e32 v16, vcc, s3, v2
	s_mov_b32 s3, 0x23000
	s_nop 0
	v_addc_co_u32_e32 v17, vcc, 0, v3, vcc
	v_add_co_u32_e32 v24, vcc, s3, v2
	s_mov_b32 s3, 0x28000
	s_nop 0
	v_addc_co_u32_e32 v25, vcc, 0, v3, vcc
	global_load_dword v18, v[2:3], off
	global_load_dword v21, v[4:5], off
	global_load_dword v20, v[6:7], off
	global_load_dword v38, v[8:9], off
	global_load_dword v19, v[12:13], off
	global_load_dword v31, v[14:15], off
	global_load_dword v30, v[16:17], off
	global_load_dword v39, v[24:25], off
	v_add_co_u32_e32 v4, vcc, s3, v2
	s_mov_b32 s3, 0x2d000
	s_nop 0
	v_addc_co_u32_e32 v5, vcc, 0, v3, vcc
	v_add_co_u32_e32 v6, vcc, s3, v2
	s_mov_b32 s3, 0x32000
	s_nop 0
	v_addc_co_u32_e32 v7, vcc, 0, v3, vcc
	v_add_co_u32_e32 v8, vcc, s3, v2
	s_mov_b32 s3, 0x37000
	s_nop 0
	v_addc_co_u32_e32 v9, vcc, 0, v3, vcc
	v_add_co_u32_e32 v12, vcc, s3, v2
	s_mov_b32 s3, 0x3c000
	s_nop 0
	v_addc_co_u32_e32 v13, vcc, 0, v3, vcc
	v_add_co_u32_e32 v14, vcc, s3, v2
	s_mov_b32 s3, 0x41000
	s_nop 0
	v_addc_co_u32_e32 v15, vcc, 0, v3, vcc
	v_add_co_u32_e32 v16, vcc, s3, v2
	s_mov_b32 s3, 0x46000
	s_nop 0
	v_addc_co_u32_e32 v17, vcc, 0, v3, vcc
	v_add_co_u32_e32 v24, vcc, s3, v2
	s_mov_b32 s3, 0x4b000
	s_nop 0
	v_addc_co_u32_e32 v25, vcc, 0, v3, vcc
	v_add_co_u32_e32 v26, vcc, s3, v2
	s_mov_b32 s3, 0x50000
	s_nop 0
	v_addc_co_u32_e32 v27, vcc, 0, v3, vcc
	global_load_dword v40, v[4:5], off
	global_load_dword v43, v[6:7], off
	global_load_dword v42, v[8:9], off
	global_load_dword v46, v[12:13], off
	global_load_dword v41, v[14:15], off
	global_load_dword v45, v[16:17], off
	global_load_dword v44, v[24:25], off
	global_load_dword v47, v[26:27], off
	v_add_co_u32_e32 v4, vcc, s3, v2
	s_mov_b32 s3, 0x55000
	s_nop 0
	v_addc_co_u32_e32 v5, vcc, 0, v3, vcc
	v_add_co_u32_e32 v6, vcc, s3, v2
	s_mov_b32 s3, 0x5a000
	s_nop 0
	v_addc_co_u32_e32 v7, vcc, 0, v3, vcc
	v_add_co_u32_e32 v8, vcc, s3, v2
	s_mov_b32 s3, 0x5f000
	s_nop 0
	v_addc_co_u32_e32 v9, vcc, 0, v3, vcc
	v_add_co_u32_e32 v12, vcc, s3, v2
	s_mov_b32 s3, 0x64000
	s_nop 0
	v_addc_co_u32_e32 v13, vcc, 0, v3, vcc
	v_add_co_u32_e32 v14, vcc, s3, v2
	s_mov_b32 s3, 0x69000
	s_nop 0
	v_addc_co_u32_e32 v15, vcc, 0, v3, vcc
	v_add_co_u32_e32 v16, vcc, s3, v2
	s_mov_b32 s3, 0x6e000
	s_nop 0
	v_addc_co_u32_e32 v17, vcc, 0, v3, vcc
	v_add_co_u32_e32 v24, vcc, s3, v2
	s_mov_b32 s3, 0x73000
	s_nop 0
	v_addc_co_u32_e32 v25, vcc, 0, v3, vcc
	v_add_co_u32_e32 v26, vcc, s3, v2
	s_mov_b32 s3, 0x78000
	s_nop 0
	v_addc_co_u32_e32 v27, vcc, 0, v3, vcc
	global_load_dword v55, v[4:5], off
	global_load_dword v58, v[6:7], off
	global_load_dword v57, v[8:9], off
	global_load_dword v61, v[12:13], off
	global_load_dword v56, v[14:15], off
	global_load_dword v60, v[16:17], off
	global_load_dword v59, v[24:25], off
	global_load_dword v62, v[26:27], off
	v_add_co_u32_e32 v4, vcc, s3, v2
	s_mov_b32 s3, 0x7d000
	s_nop 0
	v_addc_co_u32_e32 v5, vcc, 0, v3, vcc
	v_add_co_u32_e32 v6, vcc, s3, v2
	s_mov_b32 s3, 0x82000
	s_nop 0
	v_addc_co_u32_e32 v7, vcc, 0, v3, vcc
	v_add_co_u32_e32 v8, vcc, s3, v2
	s_mov_b32 s3, 0x87000
	s_nop 0
	v_addc_co_u32_e32 v9, vcc, 0, v3, vcc
	v_add_co_u32_e32 v12, vcc, s3, v2
	s_mov_b32 s3, 0x8c000
	s_nop 0
	v_addc_co_u32_e32 v13, vcc, 0, v3, vcc
	v_add_co_u32_e32 v14, vcc, s3, v2
	s_mov_b32 s3, 0x91000
	s_nop 0
	v_addc_co_u32_e32 v15, vcc, 0, v3, vcc
	v_add_co_u32_e32 v16, vcc, s3, v2
	s_cmp_eq_u64 s[60:61], 0
	s_nop 0
	v_addc_co_u32_e32 v17, vcc, 0, v3, vcc
	v_add_co_u32_e32 v24, vcc, 0x96000, v2
	s_nop 1
	v_addc_co_u32_e32 v25, vcc, 0, v3, vcc
	v_add_co_u32_e32 v2, vcc, 0x9b000, v2
	s_nop 1
	v_addc_co_u32_e32 v3, vcc, 0, v3, vcc
	global_load_dword v70, v[4:5], off
	global_load_dword v74, v[6:7], off
	global_load_dword v73, v[8:9], off
	global_load_dword v77, v[12:13], off
	global_load_dword v72, v[14:15], off
	global_load_dword v76, v[16:17], off
	global_load_dword v75, v[24:25], off
	global_load_dword v78, v[2:3], off
	s_cbranch_scc1 .LBB0_21
	s_ashr_i32 s7, s6, 31
	s_lshl_b64 s[6:7], s[6:7], 2
	s_add_u32 s6, s60, s6
	v_lshlrev_b32_e32 v2, 5, v32
	s_addc_u32 s7, s61, s7
	v_and_b32_e32 v11, 0xe0, v2
	global_load_dwordx4 v[6:9], v11, s[6:7]
	global_load_dwordx4 v[2:5], v11, s[6:7] offset:16
	s_lshl_b32 s17, s33, 3
	s_andn2_b64 vcc, exec, s[4:5]
	s_add_i32 s3, s17, 0xfffffe00
	s_cbranch_vccz .LBB0_22
	s_branch .LBB0_61

; __device__ __forceinline__ void tr_load(const TrDesc& d, int lane, TrRegs& t) {
;     const int nblk = d.N / 32, kb = d.item / nblk, nb = d.item - kb * nblk, k0 = 64 * kb, n0 = 32 * nb;
;     const float* src = d.W + (size_t)(k0 + (lane >> 5)) * d.N + n0 + (lane & 31);
; #pragma unroll
;     for (int i = 0; i < 32; ++i) t.v[i] = __builtin_nontemporal_load(src + (size_t)(2 * i) * d.N);
;     const int c = lane & 7;
;     t.g0 = (f32x4){1.f, 1.f, 1.f, 1.f}; t.g1 = t.g0;
;     if (d.gs) { t.g0 = *(const f32x4*)(d.gs + k0 + 8 * c); t.g1 = *(const f32x4*)(d.gs + k0 + 8 * c + 4); }
; }
; __global__ void __launch_bounds__(NWAVES * 64, 2) hymba_fwd(Args a) {
;     ...
;             while (it < NITEMS) {
;                 const int nx = it + NCW; const bool more = nx < NITEMS;
;                 if (more) { EARLY_DESC(dn, nx); tr_load(dn, lane, tn); }
.LBB0_24:
	s_add_i32 s9, s17, s16
	s_addk_i32 s9, 0xfe00
	s_cmpk_gt_i32 s9, 0x9ff
	s_cbranch_scc1 .LBB0_29
	s_mul_hi_i32 s6, s9, 0x66666667
	s_lshr_b32 s7, s6, 31
	s_ashr_i32 s6, s6, 5
	s_add_i32 s7, s6, s7
	s_lshl_b32 s6, s7, 6
	s_mulk_i32 s7, 0xf600
	s_add_i32 s10, s20, s7
	v_or_b32_e32 v12, s6, v1
	v_mov_b64_e32 v[10:11], s[62:63]
	v_mad_i64_i32 v[10:11], s[54:55], v12, s22, v[10:11]
	s_ashr_i32 s11, s10, 31
	v_lshl_add_u64 v[10:11], s[10:11], 2, v[10:11]
	v_mov_b32_e32 v29, v25
	v_lshl_add_u64 v[10:11], v[10:11], 0, v[28:29]
	v_add_co_u32_e32 v12, vcc, s23, v10
	s_nop 1
	v_addc_co_u32_e32 v13, vcc, 0, v11, vcc
	v_add_co_u32_e32 v14, vcc, s24, v10
	s_nop 1
	v_addc_co_u32_e32 v15, vcc, 0, v11, vcc
	v_add_co_u32_e32 v16, vcc, s25, v10
	s_nop 1
	v_addc_co_u32_e32 v17, vcc, 0, v11, vcc
	v_add_co_u32_e32 v52, vcc, s26, v10
	s_nop 1
	v_addc_co_u32_e32 v53, vcc, 0, v11, vcc
	v_add_co_u32_e32 v64, vcc, s27, v10
	s_nop 1
	v_addc_co_u32_e32 v65, vcc, 0, v11, vcc
	v_add_co_u32_e32 v66, vcc, s28, v10
	s_nop 1
	v_addc_co_u32_e32 v67, vcc, 0, v11, vcc
	v_add_co_u32_e32 v68, vcc, s29, v10
	s_nop 1
	v_addc_co_u32_e32 v69, vcc, 0, v11, vcc
	global_load_dword v29, v[10:11], off
	global_load_dword v48, v[12:13], off
	global_load_dword v49, v[14:15], off
	global_load_dword v50, v[16:17], off
	global_load_dword v51, v[52:53], off
	s_nop 0
	global_load_dword v52, v[64:65], off
	global_load_dword v53, v[66:67], off
	global_load_dword v54, v[68:69], off
	v_add_co_u32_e32 v12, vcc, s30, v10
	s_nop 1
	v_addc_co_u32_e32 v13, vcc, 0, v11, vcc
	v_add_co_u32_e32 v14, vcc, s31, v10
	s_nop 1
	v_addc_co_u32_e32 v15, vcc, 0, v11, vcc
	v_add_co_u32_e32 v16, vcc, s34, v10
	s_nop 1
	v_addc_co_u32_e32 v17, vcc, 0, v11, vcc
	v_add_co_u32_e32 v66, vcc, s35, v10
	s_nop 1
	v_addc_co_u32_e32 v67, vcc, 0, v11, vcc
	v_add_co_u32_e32 v68, vcc, s36, v10
	s_nop 1
	v_addc_co_u32_e32 v69, vcc, 0, v11, vcc
	v_add_co_u32_e32 v80, vcc, s37, v10
	s_nop 1
	v_addc_co_u32_e32 v81, vcc, 0, v11, vcc
	v_add_co_u32_e32 v82, vcc, s38, v10
	s_nop 1
	v_addc_co_u32_e32 v83, vcc, 0, v11, vcc
	v_add_co_u32_e32 v84, vcc, s39, v10
	s_nop 1
	v_addc_co_u32_e32 v85, vcc, 0, v11, vcc
	global_load_dword v63, v[12:13], off
	global_load_dword v64, v[14:15], off
	global_load_dword v65, v[16:17], off
	s_nop 0
	global_load_dword v66, v[66:67], off
	s_nop 0
	global_load_dword v67, v[68:69], off
	s_nop 0
	global_load_dword v68, v[80:81], off
	global_load_dword v69, v[82:83], off
	global_load_dword v71, v[84:85], off
	v_add_co_u32_e32 v12, vcc, s40, v10
	s_nop 1
	v_addc_co_u32_e32 v13, vcc, 0, v11, vcc
	v_add_co_u32_e32 v14, vcc, s41, v10
	s_nop 1
	v_addc_co_u32_e32 v15, vcc, 0, v11, vcc
	v_add_co_u32_e32 v16, vcc, s42, v10
	s_nop 1
	v_addc_co_u32_e32 v17, vcc, 0, v11, vcc
	v_add_co_u32_e32 v80, vcc, s43, v10
	s_nop 1
	v_addc_co_u32_e32 v81, vcc, 0, v11, vcc
	v_add_co_u32_e32 v86, vcc, s44, v10
	s_nop 1
	v_addc_co_u32_e32 v87, vcc, 0, v11, vcc
	v_add_co_u32_e32 v88, vcc, s45, v10
	s_nop 1
	v_addc_co_u32_e32 v89, vcc, 0, v11, vcc
	v_add_co_u32_e32 v90, vcc, s46, v10
	s_nop 1
	v_addc_co_u32_e32 v91, vcc, 0, v11, vcc
	v_add_co_u32_e32 v92, vcc, s47, v10
	s_nop 1
	v_addc_co_u32_e32 v93, vcc, 0, v11, vcc
	global_load_dword v85, v[12:13], off
	global_load_dword v84, v[14:15], off
	global_load_dword v83, v[16:17], off
	global_load_dword v82, v[80:81], off
	s_nop 0
	global_load_dword v81, v[86:87], off
	global_load_dword v80, v[88:89], off
	global_load_dword v79, v[90:91], off
	s_nop 0
	global_load_dword v86, v[92:93], off
	v_add_co_u32_e32 v12, vcc, s48, v10
	s_nop 1
	v_addc_co_u32_e32 v13, vcc, 0, v11, vcc
	v_add_co_u32_e32 v14, vcc, s49, v10
	s_nop 1
	v_addc_co_u32_e32 v15, vcc, 0, v11, vcc
	v_add_co_u32_e32 v16, vcc, s50, v10
	s_nop 1
	v_addc_co_u32_e32 v17, vcc, 0, v11, vcc
	v_add_co_u32_e32 v88, vcc, s51, v10
	s_nop 1
	v_addc_co_u32_e32 v89, vcc, 0, v11, vcc
	v_add_co_u32_e32 v94, vcc, s52, v10
	s_nop 1
	v_addc_co_u32_e32 v95, vcc, 0, v11, vcc
	v_add_co_u32_e32 v96, vcc, 0x91000, v10
	s_nop 1
	v_addc_co_u32_e32 v97, vcc, 0, v11, vcc
	v_add_co_u32_e32 v98, vcc, 0x96000, v10
	s_nop 1
	v_addc_co_u32_e32 v99, vcc, 0, v11, vcc
	v_add_co_u32_e32 v10, vcc, 0x9b000, v10
	s_nop 1
	v_addc_co_u32_e32 v11, vcc, 0, v11, vcc
	global_load_dword v93, v[12:13], off
	global_load_dword v92, v[14:15], off
	global_load_dword v91, v[16:17], off
	global_load_dword v90, v[88:89], off
	s_nop 0
	global_load_dword v89, v[94:95], off
	global_load_dword v88, v[96:97], off
	global_load_dword v87, v[98:99], off
	s_nop 0
	global_load_dword v94, v[10:11], off
	s_andn2_b64 vcc, exec, s[4:5]
	s_cbranch_vccnz .LBB0_27
	s_ashr_i32 s7, s6, 31
	v_lshl_add_u64 v[10:11], s[6:7], 2, v[26:27]
	global_load_dwordx4 v[14:17], v[10:11], off
	s_nop 0
	global_load_dwordx4 v[10:13], v[10:11], off offset:16
	s_branch .LBB0_28

; __device__ __forceinline__ void tr_load(const TrDesc& d, int lane, TrRegs& t) {
;     const int nblk = d.N / 32, kb = d.item / nblk, nb = d.item - kb * nblk, k0 = 64 * kb, n0 = 32 * nb;
;     const float* src = d.W + (size_t)(k0 + (lane >> 5)) * d.N + n0 + (lane & 31);
; #pragma unroll
;     for (int i = 0; i < 32; ++i) t.v[i] = __builtin_nontemporal_load(src + (size_t)(2 * i) * d.N);
;     const int c = lane & 7;
;     t.g0 = (f32x4){1.f, 1.f, 1.f, 1.f}; t.g1 = t.g0;
;     if (d.gs) { t.g0 = *(const f32x4*)(d.gs + k0 + 8 * c); t.g1 = *(const f32x4*)(d.gs + k0 + 8 * c + 4); }
; }
; __global__ void __launch_bounds__(NWAVES * 64, 2) hymba_fwd(Args a) {
;     ...
;             TrDesc dc, dn; TrRegs tc, tn;
;             const int it_hi = (bx >= G / 2) ? NIT : (bx < G / 4 ? 1536 : (I_GLU + I_O));
;             int it = (bx >= G / 2) ? (I_GLU + I_O) + cw : (bx < G / 4 ? cw : 1536 + (cw - 512));
;             const int NCWx = (bx >= G / 2) ? NCW : 512;
;             if (it < it_hi) { FFN_DESC(dc, it); tr_load(dc, lane, tc); }
.LBB0_458:
	s_lshr_b32 s5, s0, 5
	v_cvt_f32_u32_e32 v2, s5
	s_sub_i32 s16, 0, s5
	s_abs_i32 s15, s24
	s_ashr_i32 s14, s24, 31
	v_rcp_iflag_f32_e32 v2, v2
	v_lshrrev_b32_e32 v3, 5, v11
	v_and_b32_e32 v4, 31, v10
	v_lshlrev_b32_e32 v4, 2, v4
	v_mul_f32_e32 v2, 0x4f7ffffe, v2
	v_cvt_u32_f32_e32 v2, v2
	v_mov_b32_e32 v5, 0
	v_readfirstlane_b32 s17, v2
	s_mul_i32 s16, s16, s17
	s_mul_hi_u32 s16, s17, s16
	s_add_i32 s17, s17, s16
	s_mul_hi_u32 s16, s15, s17
	s_mul_i32 s17, s16, s5
	s_sub_i32 s15, s15, s17
	s_add_i32 s18, s16, 1
	s_sub_i32 s17, s15, s5
	s_cmp_ge_u32 s15, s5
	s_cselect_b32 s16, s18, s16
	s_cselect_b32 s15, s17, s15
	s_add_i32 s17, s16, 1
	s_cmp_ge_u32 s15, s5
	s_cselect_b32 s15, s17, s16
	s_xor_b32 s15, s15, s14
	s_sub_i32 s14, s15, s14
	s_mul_i32 s5, s14, s5
	s_lshl_b32 s14, s14, 6
	s_sub_i32 s5, s24, s5
	v_or_b32_e32 v2, s14, v3
	s_ashr_i32 s15, s14, 31
	s_lshl_b32 s16, s5, 5
	s_mul_i32 s5, s15, s0
	v_mad_u64_u32 v[2:3], s[18:19], v2, s0, 0
	v_add_u32_e32 v3, s5, v3
	v_lshl_add_u64 v[2:3], v[2:3], 2, s[12:13]
	s_ashr_i32 s17, s16, 31
	v_lshl_add_u64 v[2:3], s[16:17], 2, v[2:3]
	v_lshl_add_u64 v[2:3], v[2:3], 0, v[4:5]
	s_lshl_b64 s[12:13], s[0:1], 3
	v_lshl_add_u64 v[4:5], v[2:3], 0, s[12:13]
	v_lshl_add_u64 v[6:7], v[4:5], 0, s[12:13]
	v_lshl_add_u64 v[8:9], v[6:7], 0, s[12:13]
	v_lshl_add_u64 v[12:13], v[8:9], 0, s[12:13]
	v_lshl_add_u64 v[14:15], v[12:13], 0, s[12:13]
	v_lshl_add_u64 v[16:17], v[14:15], 0, s[12:13]
	v_lshl_add_u64 v[18:19], v[16:17], 0, s[12:13]
	global_load_dword v29, v[2:3], off
	global_load_dword v32, v[4:5], off
	global_load_dword v33, v[6:7], off
	global_load_dword v34, v[8:9], off
	global_load_dword v35, v[12:13], off
	global_load_dword v36, v[14:15], off
	global_load_dword v37, v[16:17], off
	global_load_dword v38, v[18:19], off
	v_lshl_add_u64 v[2:3], v[18:19], 0, s[12:13]
	global_load_dword v39, v[2:3], off
	v_lshl_add_u64 v[2:3], v[2:3], 0, s[12:13]
	global_load_dword v40, v[2:3], off
	v_lshl_add_u64 v[2:3], v[2:3], 0, s[12:13]
	global_load_dword v41, v[2:3], off
	v_lshl_add_u64 v[2:3], v[2:3], 0, s[12:13]
	global_load_dword v42, v[2:3], off
	v_lshl_add_u64 v[2:3], v[2:3], 0, s[12:13]
	global_load_dword v43, v[2:3], off
	v_lshl_add_u64 v[2:3], v[2:3], 0, s[12:13]
	global_load_dword v44, v[2:3], off
	v_lshl_add_u64 v[2:3], v[2:3], 0, s[12:13]
	global_load_dword v45, v[2:3], off
	v_lshl_add_u64 v[2:3], v[2:3], 0, s[12:13]
	global_load_dword v46, v[2:3], off
	v_lshl_add_u64 v[2:3], v[2:3], 0, s[12:13]
	global_load_dword v47, v[2:3], off
	v_lshl_add_u64 v[2:3], v[2:3], 0, s[12:13]
	global_load_dword v48, v[2:3], off
	v_lshl_add_u64 v[2:3], v[2:3], 0, s[12:13]
	global_load_dword v49, v[2:3], off
	v_lshl_add_u64 v[2:3], v[2:3], 0, s[12:13]
	global_load_dword v50, v[2:3], off
	v_lshl_add_u64 v[2:3], v[2:3], 0, s[12:13]
	global_load_dword v51, v[2:3], off
	v_lshl_add_u64 v[2:3], v[2:3], 0, s[12:13]
	global_load_dword v52, v[2:3], off
	v_lshl_add_u64 v[2:3], v[2:3], 0, s[12:13]
	global_load_dword v53, v[2:3], off
	v_lshl_add_u64 v[2:3], v[2:3], 0, s[12:13]
	global_load_dword v54, v[2:3], off
	v_lshl_add_u64 v[2:3], v[2:3], 0, s[12:13]
	global_load_dword v55, v[2:3], off
	v_lshl_add_u64 v[2:3], v[2:3], 0, s[12:13]
	global_load_dword v56, v[2:3], off
	v_lshl_add_u64 v[2:3], v[2:3], 0, s[12:13]
	global_load_dword v57, v[2:3], off
	v_lshl_add_u64 v[2:3], v[2:3], 0, s[12:13]
	global_load_dword v58, v[2:3], off
	v_lshl_add_u64 v[2:3], v[2:3], 0, s[12:13]
	global_load_dword v59, v[2:3], off
	v_lshl_add_u64 v[2:3], v[2:3], 0, s[12:13]
	global_load_dword v60, v[2:3], off
	v_lshl_add_u64 v[2:3], v[2:3], 0, s[12:13]
	global_load_dword v61, v[2:3], off
	v_lshl_add_u64 v[2:3], v[2:3], 0, s[12:13]
	global_load_dword v62, v[2:3], off
	s_cmp_eq_u64 s[10:11], 0
	s_cbranch_scc1 .LBB0_460
	s_lshl_b64 s[12:13], s[14:15], 2
	s_add_u32 s10, s10, s12
	v_lshlrev_b32_e32 v2, 5, v11
	s_addc_u32 s11, s11, s13
	v_and_b32_e32 v2, 0xe0, v2
	global_load_dwordx4 v[6:9], v2, s[10:11] offset:16
	s_nop 0
	global_load_dwordx4 v[2:5], v2, s[10:11]
	s_branch .LBB0_461

; __device__ __forceinline__ void tr_load(const TrDesc& d, int lane, TrRegs& t) {
;     const int nblk = d.N / 32, kb = d.item / nblk, nb = d.item - kb * nblk, k0 = 64 * kb, n0 = 32 * nb;
;     const float* src = d.W + (size_t)(k0 + (lane >> 5)) * d.N + n0 + (lane & 31);
; #pragma unroll
;     for (int i = 0; i < 32; ++i) t.v[i] = __builtin_nontemporal_load(src + (size_t)(2 * i) * d.N);
;     const int c = lane & 7;
;     t.g0 = (f32x4){1.f, 1.f, 1.f, 1.f}; t.g1 = t.g0;
;     if (d.gs) { t.g0 = *(const f32x4*)(d.gs + k0 + 8 * c); t.g1 = *(const f32x4*)(d.gs + k0 + 8 * c + 4); }
; }
; __global__ void __launch_bounds__(NWAVES * 64, 2) hymba_fwd(Args a) {
;     ...
;             while (it < it_hi) {
;                 const int nx = it + NCWx; const bool more = nx < it_hi;
;                 if (more) { FFN_DESC(dn, nx); tr_load(dn, lane, tn); }
.LBB0_477:
	s_lshr_b32 s20, s8, 5
	v_cvt_f32_u32_e32 v11, s20
	s_sub_i32 s31, 0, s20
	s_abs_i32 s30, s27
	s_ashr_i32 s21, s27, 31
	v_rcp_iflag_f32_e32 v11, v11
	s_nop 0
	v_mul_f32_e32 v11, 0x4f7ffffe, v11
	v_cvt_u32_f32_e32 v11, v11
	s_nop 0
	v_readfirstlane_b32 s34, v11
	s_mul_i32 s31, s31, s34
	s_mul_hi_u32 s31, s34, s31
	s_add_i32 s34, s34, s31
	s_mul_hi_u32 s31, s30, s34
	s_mul_i32 s34, s31, s20
	s_sub_i32 s30, s30, s34
	s_add_i32 s35, s31, 1
	s_sub_i32 s34, s30, s20
	s_cmp_ge_u32 s30, s20
	s_cselect_b32 s31, s35, s31
	s_cselect_b32 s30, s34, s30
	s_add_i32 s34, s31, 1
	s_cmp_ge_u32 s30, s20
	s_cselect_b32 s30, s34, s31
	s_xor_b32 s30, s30, s21
	s_sub_i32 s21, s30, s21
	s_mul_i32 s30, s21, s20
	s_lshl_b32 s20, s21, 6
	v_or_b32_e32 v11, s20, v63
	s_ashr_i32 s21, s20, 31
	s_sub_i32 s30, s27, s30
	s_mul_i32 s31, s21, s8
	v_mad_u64_u32 v[12:13], s[34:35], v11, s8, 0
	s_lshl_b32 s30, s30, 5
	v_add_u32_e32 v13, s31, v13
	v_lshl_add_u64 v[12:13], v[12:13], 2, s[18:19]
	s_ashr_i32 s31, s30, 31
	v_lshl_add_u64 v[12:13], s[30:31], 2, v[12:13]
	v_lshl_add_u64 v[12:13], v[12:13], 0, v[26:27]
	s_lshl_b64 s[18:19], s[8:9], 3
	v_lshl_add_u64 v[14:15], v[12:13], 0, s[18:19]
	v_lshl_add_u64 v[16:17], v[14:15], 0, s[18:19]
	v_lshl_add_u64 v[18:19], v[16:17], 0, s[18:19]
	v_lshl_add_u64 v[20:21], v[18:19], 0, s[18:19]
	v_lshl_add_u64 v[22:23], v[20:21], 0, s[18:19]
	v_lshl_add_u64 v[24:25], v[22:23], 0, s[18:19]
	v_lshl_add_u64 v[78:79], v[24:25], 0, s[18:19]
	global_load_dword v70, v[12:13], off
	global_load_dword v71, v[14:15], off
	global_load_dword v72, v[16:17], off
	global_load_dword v73, v[18:19], off
	global_load_dword v74, v[20:21], off
	global_load_dword v75, v[22:23], off
	global_load_dword v76, v[24:25], off
	global_load_dword v77, v[78:79], off
	v_lshl_add_u64 v[12:13], v[78:79], 0, s[18:19]
	global_load_dword v78, v[12:13], off
	v_lshl_add_u64 v[12:13], v[12:13], 0, s[18:19]
	global_load_dword v79, v[12:13], off
	v_lshl_add_u64 v[12:13], v[12:13], 0, s[18:19]
	global_load_dword v80, v[12:13], off
	v_lshl_add_u64 v[12:13], v[12:13], 0, s[18:19]
	global_load_dword v81, v[12:13], off
	v_lshl_add_u64 v[12:13], v[12:13], 0, s[18:19]
	global_load_dword v82, v[12:13], off
	v_lshl_add_u64 v[12:13], v[12:13], 0, s[18:19]
	global_load_dword v83, v[12:13], off
	v_lshl_add_u64 v[12:13], v[12:13], 0, s[18:19]
	global_load_dword v84, v[12:13], off
	v_lshl_add_u64 v[12:13], v[12:13], 0, s[18:19]
	global_load_dword v85, v[12:13], off
	v_lshl_add_u64 v[12:13], v[12:13], 0, s[18:19]
	global_load_dword v86, v[12:13], off
	v_lshl_add_u64 v[12:13], v[12:13], 0, s[18:19]
	global_load_dword v87, v[12:13], off
	v_lshl_add_u64 v[12:13], v[12:13], 0, s[18:19]
	global_load_dword v88, v[12:13], off
	v_lshl_add_u64 v[12:13], v[12:13], 0, s[18:19]
	global_load_dword v89, v[12:13], off
	v_lshl_add_u64 v[12:13], v[12:13], 0, s[18:19]
	global_load_dword v90, v[12:13], off
	v_lshl_add_u64 v[12:13], v[12:13], 0, s[18:19]
	global_load_dword v91, v[12:13], off
	v_lshl_add_u64 v[12:13], v[12:13], 0, s[18:19]
	global_load_dword v92, v[12:13], off
	v_lshl_add_u64 v[12:13], v[12:13], 0, s[18:19]
	global_load_dword v93, v[12:13], off
	v_lshl_add_u64 v[12:13], v[12:13], 0, s[18:19]
	global_load_dword v94, v[12:13], off
	v_lshl_add_u64 v[12:13], v[12:13], 0, s[18:19]
	global_load_dword v95, v[12:13], off
	v_lshl_add_u64 v[12:13], v[12:13], 0, s[18:19]
	global_load_dword v96, v[12:13], off
	v_lshl_add_u64 v[12:13], v[12:13], 0, s[18:19]
	global_load_dword v97, v[12:13], off
	v_lshl_add_u64 v[12:13], v[12:13], 0, s[18:19]
	global_load_dword v98, v[12:13], off
	v_lshl_add_u64 v[12:13], v[12:13], 0, s[18:19]
	global_load_dword v99, v[12:13], off
	v_lshl_add_u64 v[12:13], v[12:13], 0, s[18:19]
	global_load_dword v100, v[12:13], off
	v_lshl_add_u64 v[12:13], v[12:13], 0, s[18:19]
	global_load_dword v101, v[12:13], off
	s_cmp_eq_u64 s[16:17], 0
	s_cbranch_scc1 .LBB0_479
	s_lshl_b64 s[18:19], s[20:21], 2
	s_add_u32 s16, s16, s18
	s_addc_u32 s17, s17, s19
	v_lshlrev_b32_e32 v11, 2, v28
	global_load_dwordx4 v[18:21], v11, s[16:17] offset:16
	global_load_dwordx4 v[14:17], v11, s[16:17]
	s_branch .LBB0_480
